# hosted table-quant L2 touch-ahead distance 2 rows instead of 1 (on v120 stack)
# speedup vs baseline: 1.0031x; 1.0031x over previous
; __device__ void quant_rows(const float* src, unsigned char* dst, float* scales, int row_begin, int nrows) {
;     ...
;   for (int row = row_begin + blockIdx.x * 4 + w; row < nrows; row += gridDim.x * 4) {
;     const f32x4* sp = (const f32x4*)(src + (size_t)row * 1024) + lane * 4;
;     f32x4 v[4];
;     float am = 0.f;
; #pragma unroll
;     for (int k = 0; k < 4; ++k) {
;       v[k] = sp[k];
;       am = fmaxf(am, fmaxf(fmaxf(fabsf(v[k].x), fabsf(v[k].y)), fmaxf(fabsf(v[k].z), fabsf(v[k].w))));
;     }
;     am = fmaxf(am, __shfl_xor(am, 1)); am = fmaxf(am, __shfl_xor(am, 2)); am = fmaxf(am, __shfl_xor(am, 4));
;     am = fmaxf(am, __shfl_xor(am, 8)); am = fmaxf(am, __shfl_xor(am, 16)); am = fmaxf(am, __shfl_xor(am, 32));
;     const float sc = am > 0.f ? 6.f / am : 1.f;
;     u32x2 o;
; #pragma unroll
;     for (int k = 0; k < 2; ++k) {
;       unsigned wd = 0u;
;       wd = __builtin_amdgcn_cvt_scalef32_pk_fp4_f32(wd, v[2 * k].x * sc, v[2 * k].y * sc, 1.0f, 0);
;       wd = __builtin_amdgcn_cvt_scalef32_pk_fp4_f32(wd, v[2 * k].z * sc, v[2 * k].w * sc, 1.0f, 1);
;       wd = __builtin_amdgcn_cvt_scalef32_pk_fp4_f32(wd, v[2 * k + 1].x * sc, v[2 * k + 1].y * sc, 1.0f, 2);
;       wd = __builtin_amdgcn_cvt_scalef32_pk_fp4_f32(wd, v[2 * k + 1].z * sc, v[2 * k + 1].w * sc, 1.0f, 3);
;       o[k] = wd;
;     }
;     ((u32x2*)(dst + (size_t)row * 512))[lane] = o;
;     if (lane == 0) scales[row] = am > 0.f ? am * (1.f / 6.f) : 1.f;
;   }
.LBB0_443:
	v_ashrrev_i32_e32 v3, 31, v2
	v_lshlrev_b64 v[30:31], 12, v[2:3]
	s_waitcnt vmcnt(14)
	v_lshl_add_u64 v[42:43], v[20:21], 0, v[30:31]
	s_mul_i32 s57, s86, 2
	v_add_u32_e32 v200, s57, v2
	v_cmp_gt_i32_e32 vcc, s19, v200
	s_lshl_b32 s57, s57, 12
	v_mov_b32_e32 v200, s57
	v_cndmask_b32_e32 v200, 0, v200, vcc
	v_add_co_u32_e32 v194, vcc, v200, v42
	s_nop 1
	v_addc_co_u32_e32 v195, vcc, 0, v43, vcc
	global_load_dwordx4 v[30:33], v[42:43], off
	global_load_dwordx4 v[34:37], v[42:43], off offset:16
	global_load_dwordx4 v[38:41], v[42:43], off offset:32
	s_nop 0
	global_load_dwordx4 v[42:45], v[42:43], off offset:48
	global_load_dwordx4 v[196:199], v[194:195], off
	global_load_dwordx4 v[196:199], v[194:195], off offset:16
	global_load_dwordx4 v[196:199], v[194:195], off offset:32
	global_load_dwordx4 v[196:199], v[194:195], off offset:48
	s_mov_b32 s23, 0x40c00000
	s_waitcnt vmcnt(7)
	v_max_f32_e64 v0, |v33|, |v33|
	v_max_f32_e64 v46, |v32|, |v32|
	s_waitcnt vmcnt(6)
	v_max_f32_e64 v47, |v37|, |v37|
	v_max_f32_e64 v48, |v36|, |v36|
	s_waitcnt vmcnt(5)
	v_max_f32_e64 v49, |v41|, |v41|
	v_max_f32_e64 v50, |v40|, |v40|
	s_waitcnt vmcnt(4)
	v_max_f32_e64 v51, |v45|, |v45|
	v_max_f32_e64 v52, |v44|, |v44|
	v_max_f32_e32 v0, v46, v0
	v_max_f32_e32 v46, v48, v47
	v_max_f32_e32 v47, v50, v49
	v_max_f32_e32 v48, v52, v51
	v_max3_f32 v0, |v30|, |v31|, v0
	v_max3_f32 v46, |v34|, |v35|, v46
	v_max3_f32 v47, |v38|, |v39|, v47
	v_max3_f32 v48, |v42|, |v43|, v48
	v_max3_f32 v0, v0, 0, v46
	v_max3_f32 v0, v0, v47, v48
	ds_bpermute_b32 v46, v24, v0
	v_mov_b32_e32 v47, v1
	s_waitcnt lgkmcnt(0)
	v_max_f32_e32 v46, v46, v46
	v_max_f32_e32 v0, v0, v46
	ds_bpermute_b32 v46, v25, v0
	s_waitcnt lgkmcnt(0)
	v_max_f32_e32 v46, v46, v46
	v_max_f32_e32 v0, v0, v46
	ds_bpermute_b32 v46, v26, v0
	s_waitcnt lgkmcnt(0)
	v_max_f32_e32 v46, v46, v46
	v_max_f32_e32 v0, v0, v46
	ds_bpermute_b32 v46, v27, v0
	s_waitcnt lgkmcnt(0)
	v_max_f32_e32 v46, v46, v46
	v_max_f32_e32 v0, v0, v46
	ds_bpermute_b32 v46, v28, v0
	s_waitcnt lgkmcnt(0)
	v_max_f32_e32 v46, v46, v46
	v_max_f32_e32 v0, v0, v46
	ds_bpermute_b32 v48, v29, v0
	v_mov_b32_e32 v46, v1
	s_waitcnt lgkmcnt(0)
	v_max_f32_e32 v48, v48, v48
	v_max_f32_e32 v0, v0, v48
	v_div_scale_f32 v50, s[20:21], v0, v0, s23
	v_rcp_f32_e32 v51, v50
	v_div_scale_f32 v52, vcc, s23, v0, s23
	v_lshlrev_b64 v[48:49], 9, v[2:3]
	v_fma_f32 v53, -v50, v51, 1.0
	v_fmac_f32_e32 v51, v53, v51
	v_mul_f32_e32 v53, v52, v51
	v_fma_f32 v54, -v50, v53, v52
	v_fmac_f32_e32 v53, v54, v51
	v_fma_f32 v50, -v50, v53, v52
	v_div_fmas_f32 v50, v50, v51, v53
	v_div_fixup_f32 v50, v50, v0, s23
	v_cmp_lt_f32_e32 vcc, 0, v0
	s_nop 1
	v_cndmask_b32_e32 v50, 1.0, v50, vcc
	v_mul_f32_e32 v30, v30, v50
	v_mul_f32_e32 v31, v31, v50
	v_mul_f32_e32 v38, v38, v50
	v_mul_f32_e32 v39, v39, v50
	v_mul_f32_e32 v32, v32, v50
	v_mul_f32_e32 v33, v33, v50
	v_mul_f32_e32 v40, v40, v50
	v_mul_f32_e32 v41, v41, v50
	v_cvt_scalef32_pk_fp4_f32 v46, v30, v31, 1.0
	v_cvt_scalef32_pk_fp4_f32 v47, v38, v39, 1.0
	v_mul_f32_e32 v34, v34, v50
	v_mul_f32_e32 v35, v35, v50
	v_mul_f32_e32 v42, v42, v50
	v_mul_f32_e32 v43, v43, v50
	v_cvt_scalef32_pk_fp4_f32 v46, v32, v33, 1.0 op_sel:[0,0,1,0]
	v_cvt_scalef32_pk_fp4_f32 v47, v40, v41, 1.0 op_sel:[0,0,1,0]
	v_mul_f32_e32 v36, v36, v50
	v_mul_f32_e32 v37, v37, v50
	v_mul_f32_e32 v44, v44, v50
	v_mul_f32_e32 v45, v45, v50
	v_cvt_scalef32_pk_fp4_f32 v46, v34, v35, 1.0 op_sel:[0,0,0,1]
	v_cvt_scalef32_pk_fp4_f32 v47, v42, v43, 1.0 op_sel:[0,0,0,1]
	v_cvt_scalef32_pk_fp4_f32 v46, v36, v37, 1.0 op_sel:[0,0,1,1]
	v_cvt_scalef32_pk_fp4_f32 v47, v44, v45, 1.0 op_sel:[0,0,1,1]
	v_lshl_add_u64 v[30:31], v[22:23], 0, v[48:49]
	global_store_dwordx2 v[30:31], v[46:47], off
	s_and_saveexec_b64 s[20:21], s[0:1]
	s_cbranch_execz .LBB0_442
	v_mul_f32_e32 v0, 0x3e2aaaab, v0
	v_cndmask_b32_e32 v0, 1.0, v0, vcc
	v_lshl_add_u64 v[30:31], v[2:3], 2, s[8:9]
	global_store_dword v[30:31], v0, off
	s_branch .LBB0_442

; __device__ void quant_rows(const float* src, unsigned char* dst, float* scales, int row_begin, int nrows) {
;     ...
;   for (int row = row_begin + blockIdx.x * 4 + w; row < nrows; row += gridDim.x * 4) {
;     const f32x4* sp = (const f32x4*)(src + (size_t)row * 1024) + lane * 4;
;     f32x4 v[4];
;     float am = 0.f;
; #pragma unroll
;     for (int k = 0; k < 4; ++k) {
;       v[k] = sp[k];
;       am = fmaxf(am, fmaxf(fmaxf(fabsf(v[k].x), fabsf(v[k].y)), fmaxf(fabsf(v[k].z), fabsf(v[k].w))));
;     }
;     am = fmaxf(am, __shfl_xor(am, 1)); am = fmaxf(am, __shfl_xor(am, 2)); am = fmaxf(am, __shfl_xor(am, 4));
;     am = fmaxf(am, __shfl_xor(am, 8)); am = fmaxf(am, __shfl_xor(am, 16)); am = fmaxf(am, __shfl_xor(am, 32));
;     const float sc = am > 0.f ? 6.f / am : 1.f;
;     u32x2 o;
; #pragma unroll
;     for (int k = 0; k < 2; ++k) {
;       unsigned wd = 0u;
;       wd = __builtin_amdgcn_cvt_scalef32_pk_fp4_f32(wd, v[2 * k].x * sc, v[2 * k].y * sc, 1.0f, 0);
;       wd = __builtin_amdgcn_cvt_scalef32_pk_fp4_f32(wd, v[2 * k].z * sc, v[2 * k].w * sc, 1.0f, 1);
;       wd = __builtin_amdgcn_cvt_scalef32_pk_fp4_f32(wd, v[2 * k + 1].x * sc, v[2 * k + 1].y * sc, 1.0f, 2);
;       wd = __builtin_amdgcn_cvt_scalef32_pk_fp4_f32(wd, v[2 * k + 1].z * sc, v[2 * k + 1].w * sc, 1.0f, 3);
;       o[k] = wd;
;     }
;     ((u32x2*)(dst + (size_t)row * 512))[lane] = o;
;     if (lane == 0) scales[row] = am > 0.f ? am * (1.f / 6.f) : 1.f;
;   }
.LBB0_448:
	v_ashrrev_i32_e32 v3, 31, v2
	v_lshlrev_b64 v[30:31], 12, v[2:3]
	s_waitcnt vmcnt(14)
	v_lshl_add_u64 v[42:43], v[20:21], 0, v[30:31]
	s_mul_i32 s57, s86, 2
	v_add_u32_e32 v200, s57, v2
	v_cmp_gt_i32_e32 vcc, s19, v200
	s_lshl_b32 s57, s57, 12
	v_mov_b32_e32 v200, s57
	v_cndmask_b32_e32 v200, 0, v200, vcc
	v_add_co_u32_e32 v194, vcc, v200, v42
	s_nop 1
	v_addc_co_u32_e32 v195, vcc, 0, v43, vcc
	global_load_dwordx4 v[30:33], v[42:43], off
	global_load_dwordx4 v[34:37], v[42:43], off offset:16
	global_load_dwordx4 v[38:41], v[42:43], off offset:32
	s_nop 0
	global_load_dwordx4 v[42:45], v[42:43], off offset:48
	global_load_dwordx4 v[196:199], v[194:195], off
	global_load_dwordx4 v[196:199], v[194:195], off offset:16
	global_load_dwordx4 v[196:199], v[194:195], off offset:32
	global_load_dwordx4 v[196:199], v[194:195], off offset:48
	s_mov_b32 s22, 0x40c00000
	s_waitcnt vmcnt(7)
	v_max_f32_e64 v0, |v33|, |v33|
	v_max_f32_e64 v46, |v32|, |v32|
	s_waitcnt vmcnt(6)
	v_max_f32_e64 v47, |v37|, |v37|
	v_max_f32_e64 v48, |v36|, |v36|
	s_waitcnt vmcnt(5)
	v_max_f32_e64 v49, |v41|, |v41|
	v_max_f32_e64 v50, |v40|, |v40|
	s_waitcnt vmcnt(4)
	v_max_f32_e64 v51, |v45|, |v45|
	v_max_f32_e64 v52, |v44|, |v44|
	v_max_f32_e32 v0, v46, v0
	v_max_f32_e32 v46, v48, v47
	v_max_f32_e32 v47, v50, v49
	v_max_f32_e32 v48, v52, v51
	v_max3_f32 v0, |v30|, |v31|, v0
	v_max3_f32 v46, |v34|, |v35|, v46
	v_max3_f32 v47, |v38|, |v39|, v47
	v_max3_f32 v48, |v42|, |v43|, v48
	v_max3_f32 v0, v0, 0, v46
	v_max3_f32 v0, v0, v47, v48
	ds_bpermute_b32 v46, v24, v0
	v_mov_b32_e32 v47, v1
	s_waitcnt lgkmcnt(0)
	v_max_f32_e32 v46, v46, v46
	v_max_f32_e32 v0, v0, v46
	ds_bpermute_b32 v46, v25, v0
	s_waitcnt lgkmcnt(0)
	v_max_f32_e32 v46, v46, v46
	v_max_f32_e32 v0, v0, v46
	ds_bpermute_b32 v46, v26, v0
	s_waitcnt lgkmcnt(0)
	v_max_f32_e32 v46, v46, v46
	v_max_f32_e32 v0, v0, v46
	ds_bpermute_b32 v46, v27, v0
	s_waitcnt lgkmcnt(0)
	v_max_f32_e32 v46, v46, v46
	v_max_f32_e32 v0, v0, v46
	ds_bpermute_b32 v46, v28, v0
	s_waitcnt lgkmcnt(0)
	v_max_f32_e32 v46, v46, v46
	v_max_f32_e32 v0, v0, v46
	ds_bpermute_b32 v48, v29, v0
	v_mov_b32_e32 v46, v1
	s_waitcnt lgkmcnt(0)
	v_max_f32_e32 v48, v48, v48
	v_max_f32_e32 v0, v0, v48
	v_div_scale_f32 v50, s[20:21], v0, v0, s22
	v_rcp_f32_e32 v51, v50
	v_div_scale_f32 v52, vcc, s22, v0, s22
	v_lshlrev_b64 v[48:49], 9, v[2:3]
	v_fma_f32 v53, -v50, v51, 1.0
	v_fmac_f32_e32 v51, v53, v51
	v_mul_f32_e32 v53, v52, v51
	v_fma_f32 v54, -v50, v53, v52
	v_fmac_f32_e32 v53, v54, v51
	v_fma_f32 v50, -v50, v53, v52
	v_div_fmas_f32 v50, v50, v51, v53
	v_div_fixup_f32 v50, v50, v0, s22
	v_cmp_lt_f32_e32 vcc, 0, v0
	s_nop 1
	v_cndmask_b32_e32 v50, 1.0, v50, vcc
	v_mul_f32_e32 v30, v30, v50
	v_mul_f32_e32 v31, v31, v50
	v_mul_f32_e32 v38, v38, v50
	v_mul_f32_e32 v39, v39, v50
	v_mul_f32_e32 v32, v32, v50
	v_mul_f32_e32 v33, v33, v50
	v_mul_f32_e32 v40, v40, v50
	v_mul_f32_e32 v41, v41, v50
	v_cvt_scalef32_pk_fp4_f32 v46, v30, v31, 1.0
	v_cvt_scalef32_pk_fp4_f32 v47, v38, v39, 1.0
	v_mul_f32_e32 v34, v34, v50
	v_mul_f32_e32 v35, v35, v50
	v_mul_f32_e32 v42, v42, v50
	v_mul_f32_e32 v43, v43, v50
	v_cvt_scalef32_pk_fp4_f32 v46, v32, v33, 1.0 op_sel:[0,0,1,0]
	v_cvt_scalef32_pk_fp4_f32 v47, v40, v41, 1.0 op_sel:[0,0,1,0]
	v_mul_f32_e32 v36, v36, v50
	v_mul_f32_e32 v37, v37, v50
	v_mul_f32_e32 v44, v44, v50
	v_mul_f32_e32 v45, v45, v50
	v_cvt_scalef32_pk_fp4_f32 v46, v34, v35, 1.0 op_sel:[0,0,0,1]
	v_cvt_scalef32_pk_fp4_f32 v47, v42, v43, 1.0 op_sel:[0,0,0,1]
	v_cvt_scalef32_pk_fp4_f32 v46, v36, v37, 1.0 op_sel:[0,0,1,1]
	v_cvt_scalef32_pk_fp4_f32 v47, v44, v45, 1.0 op_sel:[0,0,1,1]
	v_lshl_add_u64 v[30:31], v[22:23], 0, v[48:49]
	global_store_dwordx2 v[30:31], v[46:47], off
	s_and_saveexec_b64 s[20:21], s[0:1]
	s_cbranch_execz .LBB0_447
	v_mul_f32_e32 v0, 0x3e2aaaab, v0
	v_cndmask_b32_e32 v0, 1.0, v0, vcc
	v_lshl_add_u64 v[30:31], v[2:3], 2, s[8:9]
	global_store_dword v[30:31], v0, off
	s_branch .LBB0_447

; __device__ void quant_rows(const float* src, unsigned char* dst, float* scales, int row_begin, int nrows) {
;     ...
;   for (int row = row_begin + blockIdx.x * 4 + w; row < nrows; row += gridDim.x * 4) {
;     const f32x4* sp = (const f32x4*)(src + (size_t)row * 1024) + lane * 4;
;     f32x4 v[4];
;     float am = 0.f;
; #pragma unroll
;     for (int k = 0; k < 4; ++k) {
;       v[k] = sp[k];
;       am = fmaxf(am, fmaxf(fmaxf(fabsf(v[k].x), fabsf(v[k].y)), fmaxf(fabsf(v[k].z), fabsf(v[k].w))));
;     }
;     am = fmaxf(am, __shfl_xor(am, 1)); am = fmaxf(am, __shfl_xor(am, 2)); am = fmaxf(am, __shfl_xor(am, 4));
;     am = fmaxf(am, __shfl_xor(am, 8)); am = fmaxf(am, __shfl_xor(am, 16)); am = fmaxf(am, __shfl_xor(am, 32));
;     const float sc = am > 0.f ? 6.f / am : 1.f;
;     u32x2 o;
; #pragma unroll
;     for (int k = 0; k < 2; ++k) {
;       unsigned wd = 0u;
;       wd = __builtin_amdgcn_cvt_scalef32_pk_fp4_f32(wd, v[2 * k].x * sc, v[2 * k].y * sc, 1.0f, 0);
;       wd = __builtin_amdgcn_cvt_scalef32_pk_fp4_f32(wd, v[2 * k].z * sc, v[2 * k].w * sc, 1.0f, 1);
;       wd = __builtin_amdgcn_cvt_scalef32_pk_fp4_f32(wd, v[2 * k + 1].x * sc, v[2 * k + 1].y * sc, 1.0f, 2);
;       wd = __builtin_amdgcn_cvt_scalef32_pk_fp4_f32(wd, v[2 * k + 1].z * sc, v[2 * k + 1].w * sc, 1.0f, 3);
;       o[k] = wd;
;     }
;     ((u32x2*)(dst + (size_t)row * 512))[lane] = o;
;     if (lane == 0) scales[row] = am > 0.f ? am * (1.f / 6.f) : 1.f;
;   }
.LBB0_641:
	v_ashrrev_i32_e32 v3, 31, v2
	v_lshlrev_b64 v[30:31], 12, v[2:3]
	s_waitcnt vmcnt(14)
	v_lshl_add_u64 v[42:43], v[20:21], 0, v[30:31]
	s_mul_i32 s57, s86, 2
	v_add_u32_e32 v200, s57, v2
	v_cmp_gt_i32_e32 vcc, s19, v200
	s_lshl_b32 s57, s57, 12
	v_mov_b32_e32 v200, s57
	v_cndmask_b32_e32 v200, 0, v200, vcc
	v_add_co_u32_e32 v194, vcc, v200, v42
	s_nop 1
	v_addc_co_u32_e32 v195, vcc, 0, v43, vcc
	global_load_dwordx4 v[30:33], v[42:43], off
	global_load_dwordx4 v[34:37], v[42:43], off offset:16
	global_load_dwordx4 v[38:41], v[42:43], off offset:32
	s_nop 0
	global_load_dwordx4 v[42:45], v[42:43], off offset:48
	global_load_dwordx4 v[196:199], v[194:195], off
	global_load_dwordx4 v[196:199], v[194:195], off offset:16
	global_load_dwordx4 v[196:199], v[194:195], off offset:32
	global_load_dwordx4 v[196:199], v[194:195], off offset:48
	s_mov_b32 s24, 0x40c00000
	s_waitcnt vmcnt(7)
	v_max_f32_e64 v0, |v33|, |v33|
	v_max_f32_e64 v46, |v32|, |v32|
	s_waitcnt vmcnt(6)
	v_max_f32_e64 v47, |v37|, |v37|
	v_max_f32_e64 v48, |v36|, |v36|
	s_waitcnt vmcnt(5)
	v_max_f32_e64 v49, |v41|, |v41|
	v_max_f32_e64 v50, |v40|, |v40|
	s_waitcnt vmcnt(4)
	v_max_f32_e64 v51, |v45|, |v45|
	v_max_f32_e64 v52, |v44|, |v44|
	v_max_f32_e32 v0, v46, v0
	v_max_f32_e32 v46, v48, v47
	v_max_f32_e32 v47, v50, v49
	v_max_f32_e32 v48, v52, v51
	v_max3_f32 v0, |v30|, |v31|, v0
	v_max3_f32 v46, |v34|, |v35|, v46
	v_max3_f32 v47, |v38|, |v39|, v47
	v_max3_f32 v48, |v42|, |v43|, v48
	v_max3_f32 v0, v0, 0, v46
	v_max3_f32 v0, v0, v47, v48
	ds_bpermute_b32 v46, v24, v0
	v_mov_b32_e32 v47, v1
	s_waitcnt lgkmcnt(0)
	v_max_f32_e32 v46, v46, v46
	v_max_f32_e32 v0, v0, v46
	ds_bpermute_b32 v46, v25, v0
	s_waitcnt lgkmcnt(0)
	v_max_f32_e32 v46, v46, v46
	v_max_f32_e32 v0, v0, v46
	ds_bpermute_b32 v46, v26, v0
	s_waitcnt lgkmcnt(0)
	v_max_f32_e32 v46, v46, v46
	v_max_f32_e32 v0, v0, v46
	ds_bpermute_b32 v46, v27, v0
	s_waitcnt lgkmcnt(0)
	v_max_f32_e32 v46, v46, v46
	v_max_f32_e32 v0, v0, v46
	ds_bpermute_b32 v46, v28, v0
	s_waitcnt lgkmcnt(0)
	v_max_f32_e32 v46, v46, v46
	v_max_f32_e32 v0, v0, v46
	ds_bpermute_b32 v48, v29, v0
	v_mov_b32_e32 v46, v1
	s_waitcnt lgkmcnt(0)
	v_max_f32_e32 v48, v48, v48
	v_max_f32_e32 v0, v0, v48
	v_div_scale_f32 v50, s[22:23], v0, v0, s24
	v_rcp_f32_e32 v51, v50
	v_div_scale_f32 v52, vcc, s24, v0, s24
	v_lshlrev_b64 v[48:49], 9, v[2:3]
	v_fma_f32 v53, -v50, v51, 1.0
	v_fmac_f32_e32 v51, v53, v51
	v_mul_f32_e32 v53, v52, v51
	v_fma_f32 v54, -v50, v53, v52
	v_fmac_f32_e32 v53, v54, v51
	v_fma_f32 v50, -v50, v53, v52
	v_div_fmas_f32 v50, v50, v51, v53
	v_div_fixup_f32 v50, v50, v0, s24
	v_cmp_lt_f32_e32 vcc, 0, v0
	s_nop 1
	v_cndmask_b32_e32 v50, 1.0, v50, vcc
	v_mul_f32_e32 v30, v30, v50
	v_mul_f32_e32 v31, v31, v50
	v_mul_f32_e32 v38, v38, v50
	v_mul_f32_e32 v39, v39, v50
	v_mul_f32_e32 v32, v32, v50
	v_mul_f32_e32 v33, v33, v50
	v_mul_f32_e32 v40, v40, v50
	v_mul_f32_e32 v41, v41, v50
	v_cvt_scalef32_pk_fp4_f32 v46, v30, v31, 1.0
	v_cvt_scalef32_pk_fp4_f32 v47, v38, v39, 1.0
	v_mul_f32_e32 v34, v34, v50
	v_mul_f32_e32 v35, v35, v50
	v_mul_f32_e32 v42, v42, v50
	v_mul_f32_e32 v43, v43, v50
	v_cvt_scalef32_pk_fp4_f32 v46, v32, v33, 1.0 op_sel:[0,0,1,0]
	v_cvt_scalef32_pk_fp4_f32 v47, v40, v41, 1.0 op_sel:[0,0,1,0]
	v_mul_f32_e32 v36, v36, v50
	v_mul_f32_e32 v37, v37, v50
	v_mul_f32_e32 v44, v44, v50
	v_mul_f32_e32 v45, v45, v50
	v_cvt_scalef32_pk_fp4_f32 v46, v34, v35, 1.0 op_sel:[0,0,0,1]
	v_cvt_scalef32_pk_fp4_f32 v47, v42, v43, 1.0 op_sel:[0,0,0,1]
	v_cvt_scalef32_pk_fp4_f32 v46, v36, v37, 1.0 op_sel:[0,0,1,1]
	v_cvt_scalef32_pk_fp4_f32 v47, v44, v45, 1.0 op_sel:[0,0,1,1]
	v_lshl_add_u64 v[30:31], v[22:23], 0, v[48:49]
	global_store_dwordx2 v[30:31], v[46:47], off
	s_and_saveexec_b64 s[22:23], s[0:1]
	s_cbranch_execz .LBB0_640
	v_mul_f32_e32 v0, 0x3e2aaaab, v0
	v_cndmask_b32_e32 v0, 1.0, v0, vcc
	v_lshl_add_u64 v[30:31], v[2:3], 2, s[8:9]
	global_store_dword v[30:31], v0, off
	s_branch .LBB0_640
